# gdn_norm prompt rows rewritten by hand: one 512-column row per wave, 16-byte loads/stores, all rows of a wave in flight at once
# speedup vs baseline: 1.0228x; 1.0071x over previous
; __device__ __forceinline__ float bf2f(bf16 v) { return __uint_as_float(((unsigned)v) << 16); }
; __device__ __forceinline__ unsigned f2bf(float f) { unsigned u = __float_as_uint(f); return (u + 0x7fffu + ((u >> 16) & 1u)) >> 16; }
; __device__ __forceinline__ float siluf_(float x) { return x / (1.0f + __expf(-x)); }
; __device__ __forceinline__ void p4b_gdn_norm(const Ctx& c0, int l) {
;     ...
;     for (int it0 = gw; it0 < MPR * 8; it0 += 8 * NGW) {
;         float ov[8], zv[8];
; #pragma unroll
;         for (int u = 0; u < 8; ++u) { const int it = it0 + u * NGW; ov[u] = 0.f; zv[u] = 0.f;
;             if (it < MPR * 8) { const int hh = it & 7, m = it >> 3; ov[u] = __builtin_nontemporal_load(OG + (size_t)m * 512 + hh * 64 + lane); zv[u] = bf2f(__builtin_nontemporal_load(H + (size_t)m * HW + HGZ + hh * 64 + lane)); } }
; #pragma unroll
;         for (int u = 0; u < 8; ++u) { const int it = it0 + u * NGW;
;             if (it < MPR * 8) { const int hh = it & 7, m = it >> 3; const float ms = wave_sum_fast(ov[u] * ov[u]) * (1.f / 64.f);
;                 MIX[(size_t)m * DM + 512 + hh * 64 + lane] = (bf16)f2bf(ov[u] * rsqrtf(ms + RMS_EPS) * nw * siluf_(zv[u])); } } }
.LBB0_1526:
	s_movk_i32 s33, 0x4000
	s_cmp_gt_i32 s12, 0x3fff
	s_cbranch_scc1 .LBB0_1462
	v_readlane_b32 s2, v253, 3
	s_add_u32 s4, s23, 0x3a900000
	s_addc_u32 s5, s24, 0
	s_add_u32 s6, s13, 0xfd01600
	s_addc_u32 s7, s18, 0
	s_add_u32 s8, s19, 0x20700400
	s_addc_u32 s9, s22, 0
	s_lshl_b32 s2, s2, 3
	s_mov_b32 s3, 0x7060302
	v_lshlrev_b32_e32 v40, 5, v18
	v_lshlrev_b32_e32 v41, 4, v18
	v_and_b32_e32 v50, 7, v18
	v_lshlrev_b32_e32 v50, 5, v50
	s_waitcnt vmcnt(0)
	ds_bpermute_b32 v42, v50, v36 offset:0
	ds_bpermute_b32 v43, v50, v36 offset:4
	ds_bpermute_b32 v44, v50, v36 offset:8
	ds_bpermute_b32 v45, v50, v36 offset:12
	ds_bpermute_b32 v46, v50, v36 offset:16
	ds_bpermute_b32 v47, v50, v36 offset:20
	ds_bpermute_b32 v48, v50, v36 offset:24
	ds_bpermute_b32 v49, v50, v36 offset:28
	s_waitcnt lgkmcnt(0)
.Lgn3_pass:
	s_mov_b32 s22, s12
	s_add_i32 s23, s22, s2
	s_add_i32 s24, s23, s2
	s_add_i32 s25, s24, s2
	s_add_i32 s26, s25, s2
	s_add_i32 s27, s26, s2
	s_add_i32 s28, s27, s2
	s_add_i32 s29, s28, s2
	s_cmp_gt_i32 s22, 0x3fff
	s_cbranch_scc1 .Lgn3_ld0
	s_lshl_b32 s10, s22, 11
	s_mul_i32 s11, s22, 0x1c00
	s_add_u32 s16, s4, s10
	s_addc_u32 s17, s5, 0
	s_add_u32 s36, s6, s11
	s_addc_u32 s37, s7, 0
	global_load_dwordx4 v[56:59], v40, s[16:17] nt
	global_load_dwordx4 v[60:63], v40, s[16:17] offset:16 nt
	global_load_dwordx4 v[64:67], v41, s[36:37] nt
.Lgn3_ld0:
	s_cmp_gt_i32 s23, 0x3fff
	s_cbranch_scc1 .Lgn3_ld1
	s_lshl_b32 s10, s23, 11
	s_mul_i32 s11, s23, 0x1c00
	s_add_u32 s16, s4, s10
	s_addc_u32 s17, s5, 0
	s_add_u32 s36, s6, s11
	s_addc_u32 s37, s7, 0
	global_load_dwordx4 v[68:71], v40, s[16:17] nt
	global_load_dwordx4 v[72:75], v40, s[16:17] offset:16 nt
	global_load_dwordx4 v[76:79], v41, s[36:37] nt
.Lgn3_ld1:
	s_cmp_gt_i32 s24, 0x3fff
	s_cbranch_scc1 .Lgn3_ld2
	s_lshl_b32 s10, s24, 11
	s_mul_i32 s11, s24, 0x1c00
	s_add_u32 s16, s4, s10
	s_addc_u32 s17, s5, 0
	s_add_u32 s36, s6, s11
	s_addc_u32 s37, s7, 0
	global_load_dwordx4 v[80:83], v40, s[16:17] nt
	global_load_dwordx4 v[84:87], v40, s[16:17] offset:16 nt
	global_load_dwordx4 v[88:91], v41, s[36:37] nt
.Lgn3_ld2:
	s_cmp_gt_i32 s25, 0x3fff
	s_cbranch_scc1 .Lgn3_ld3
	s_lshl_b32 s10, s25, 11
	s_mul_i32 s11, s25, 0x1c00
	s_add_u32 s16, s4, s10
	s_addc_u32 s17, s5, 0
	s_add_u32 s36, s6, s11
	s_addc_u32 s37, s7, 0
	global_load_dwordx4 v[92:95], v40, s[16:17] nt
	global_load_dwordx4 v[96:99], v40, s[16:17] offset:16 nt
	global_load_dwordx4 v[100:103], v41, s[36:37] nt
.Lgn3_ld3:
	s_cmp_gt_i32 s26, 0x3fff
	s_cbranch_scc1 .Lgn3_ld4
	s_lshl_b32 s10, s26, 11
	s_mul_i32 s11, s26, 0x1c00
	s_add_u32 s16, s4, s10
	s_addc_u32 s17, s5, 0
	s_add_u32 s36, s6, s11
	s_addc_u32 s37, s7, 0
	global_load_dwordx4 v[104:107], v40, s[16:17] nt
	global_load_dwordx4 v[108:111], v40, s[16:17] offset:16 nt
	global_load_dwordx4 v[112:115], v41, s[36:37] nt
.Lgn3_ld4:
	s_cmp_gt_i32 s27, 0x3fff
	s_cbranch_scc1 .Lgn3_ld5
	s_lshl_b32 s10, s27, 11
	s_mul_i32 s11, s27, 0x1c00
	s_add_u32 s16, s4, s10
	s_addc_u32 s17, s5, 0
	s_add_u32 s36, s6, s11
	s_addc_u32 s37, s7, 0
	global_load_dwordx4 v[116:119], v40, s[16:17] nt
	global_load_dwordx4 v[120:123], v40, s[16:17] offset:16 nt
	global_load_dwordx4 v[124:127], v41, s[36:37] nt
.Lgn3_ld5:
	s_cmp_gt_i32 s28, 0x3fff
	s_cbranch_scc1 .Lgn3_ld6
	s_lshl_b32 s10, s28, 11
	s_mul_i32 s11, s28, 0x1c00
	s_add_u32 s16, s4, s10
	s_addc_u32 s17, s5, 0
	s_add_u32 s36, s6, s11
	s_addc_u32 s37, s7, 0
	global_load_dwordx4 v[128:131], v40, s[16:17] nt
	global_load_dwordx4 v[132:135], v40, s[16:17] offset:16 nt
	global_load_dwordx4 v[136:139], v41, s[36:37] nt
.Lgn3_ld6:
	s_cmp_gt_i32 s29, 0x3fff
	s_cbranch_scc1 .Lgn3_ld7
	s_lshl_b32 s10, s29, 11
	s_mul_i32 s11, s29, 0x1c00
	s_add_u32 s16, s4, s10
	s_addc_u32 s17, s5, 0
	s_add_u32 s36, s6, s11
	s_addc_u32 s37, s7, 0
	global_load_dwordx4 v[140:143], v40, s[16:17] nt
	global_load_dwordx4 v[144:147], v40, s[16:17] offset:16 nt
	global_load_dwordx4 v[148:151], v41, s[36:37] nt
.Lgn3_ld7:
	s_waitcnt vmcnt(0)
	v_mul_f32_e32 v152, v56, v56
	v_fmac_f32_e32 v152, v57, v57
	v_fmac_f32_e32 v152, v58, v58
	v_fmac_f32_e32 v152, v59, v59
	v_fmac_f32_e32 v152, v60, v60
	v_fmac_f32_e32 v152, v61, v61
	v_fmac_f32_e32 v152, v62, v62
	v_fmac_f32_e32 v152, v63, v63
	v_mul_f32_e32 v153, v68, v68
	v_fmac_f32_e32 v153, v69, v69
	v_fmac_f32_e32 v153, v70, v70
	v_fmac_f32_e32 v153, v71, v71
	v_fmac_f32_e32 v153, v72, v72
	v_fmac_f32_e32 v153, v73, v73
	v_fmac_f32_e32 v153, v74, v74
	v_fmac_f32_e32 v153, v75, v75
	v_mul_f32_e32 v154, v80, v80
	v_fmac_f32_e32 v154, v81, v81
	v_fmac_f32_e32 v154, v82, v82
	v_fmac_f32_e32 v154, v83, v83
	v_fmac_f32_e32 v154, v84, v84
	v_fmac_f32_e32 v154, v85, v85
	v_fmac_f32_e32 v154, v86, v86
	v_fmac_f32_e32 v154, v87, v87
	v_mul_f32_e32 v155, v92, v92
	v_fmac_f32_e32 v155, v93, v93
	v_fmac_f32_e32 v155, v94, v94
	v_fmac_f32_e32 v155, v95, v95
	v_fmac_f32_e32 v155, v96, v96
	v_fmac_f32_e32 v155, v97, v97
	v_fmac_f32_e32 v155, v98, v98
	v_fmac_f32_e32 v155, v99, v99
	v_mul_f32_e32 v156, v104, v104
	v_fmac_f32_e32 v156, v105, v105
	v_fmac_f32_e32 v156, v106, v106
	v_fmac_f32_e32 v156, v107, v107
	v_fmac_f32_e32 v156, v108, v108
	v_fmac_f32_e32 v156, v109, v109
	v_fmac_f32_e32 v156, v110, v110
	v_fmac_f32_e32 v156, v111, v111
	v_mul_f32_e32 v157, v116, v116
	v_fmac_f32_e32 v157, v117, v117
	v_fmac_f32_e32 v157, v118, v118
	v_fmac_f32_e32 v157, v119, v119
	v_fmac_f32_e32 v157, v120, v120
	v_fmac_f32_e32 v157, v121, v121
	v_fmac_f32_e32 v157, v122, v122
	v_fmac_f32_e32 v157, v123, v123
	v_mul_f32_e32 v158, v128, v128
	v_fmac_f32_e32 v158, v129, v129
	v_fmac_f32_e32 v158, v130, v130
	v_fmac_f32_e32 v158, v131, v131
	v_fmac_f32_e32 v158, v132, v132
; __device__ __forceinline__ float bf2f(bf16 v) { return __uint_as_float(((unsigned)v) << 16); }
; __device__ __forceinline__ unsigned f2bf(float f) { unsigned u = __float_as_uint(f); return (u + 0x7fffu + ((u >> 16) & 1u)) >> 16; }
; __device__ __forceinline__ float siluf_(float x) { return x / (1.0f + __expf(-x)); }
; __device__ __forceinline__ void p4b_gdn_norm(const Ctx& c0, int l) {
;     ...
;             if (it < MPR * 8) { const int hh = it & 7, m = it >> 3; ov[u] = __builtin_nontemporal_load(OG + (size_t)m * 512 + hh * 64 + lane); zv[u] = bf2f(__builtin_nontemporal_load(H + (size_t)m * HW + HGZ + hh * 64 + lane)); } }
; #pragma unroll
;         for (int u = 0; u < 8; ++u) { const int it = it0 + u * NGW;
;             if (it < MPR * 8) { const int hh = it & 7, m = it >> 3; const float ms = wave_sum_fast(ov[u] * ov[u]) * (1.f / 64.f);
;                 MIX[(size_t)m * DM + 512 + hh * 64 + lane] = (bf16)f2bf(ov[u] * rsqrtf(ms + RMS_EPS) * nw * siluf_(zv[u])); } } }
	v_fmac_f32_e32 v158, v133, v133
	v_fmac_f32_e32 v158, v134, v134
	v_fmac_f32_e32 v158, v135, v135
	v_mul_f32_e32 v159, v140, v140
	v_fmac_f32_e32 v159, v141, v141
	v_fmac_f32_e32 v159, v142, v142
	v_fmac_f32_e32 v159, v143, v143
	v_fmac_f32_e32 v159, v144, v144
	v_fmac_f32_e32 v159, v145, v145
	v_fmac_f32_e32 v159, v146, v146
	v_fmac_f32_e32 v159, v147, v147
	s_nop 1
	v_add_f32_dpp v152, v152, v152 quad_perm:[1,0,3,2] row_mask:0xf bank_mask:0xf bound_ctrl:1
	v_add_f32_dpp v153, v153, v153 quad_perm:[1,0,3,2] row_mask:0xf bank_mask:0xf bound_ctrl:1
	v_add_f32_dpp v154, v154, v154 quad_perm:[1,0,3,2] row_mask:0xf bank_mask:0xf bound_ctrl:1
	v_add_f32_dpp v155, v155, v155 quad_perm:[1,0,3,2] row_mask:0xf bank_mask:0xf bound_ctrl:1
	v_add_f32_dpp v156, v156, v156 quad_perm:[1,0,3,2] row_mask:0xf bank_mask:0xf bound_ctrl:1
	v_add_f32_dpp v157, v157, v157 quad_perm:[1,0,3,2] row_mask:0xf bank_mask:0xf bound_ctrl:1
	v_add_f32_dpp v158, v158, v158 quad_perm:[1,0,3,2] row_mask:0xf bank_mask:0xf bound_ctrl:1
	v_add_f32_dpp v159, v159, v159 quad_perm:[1,0,3,2] row_mask:0xf bank_mask:0xf bound_ctrl:1
	s_nop 1
	v_add_f32_dpp v152, v152, v152 quad_perm:[2,3,0,1] row_mask:0xf bank_mask:0xf bound_ctrl:1
	v_add_f32_dpp v153, v153, v153 quad_perm:[2,3,0,1] row_mask:0xf bank_mask:0xf bound_ctrl:1
	v_add_f32_dpp v154, v154, v154 quad_perm:[2,3,0,1] row_mask:0xf bank_mask:0xf bound_ctrl:1
	v_add_f32_dpp v155, v155, v155 quad_perm:[2,3,0,1] row_mask:0xf bank_mask:0xf bound_ctrl:1
	v_add_f32_dpp v156, v156, v156 quad_perm:[2,3,0,1] row_mask:0xf bank_mask:0xf bound_ctrl:1
	v_add_f32_dpp v157, v157, v157 quad_perm:[2,3,0,1] row_mask:0xf bank_mask:0xf bound_ctrl:1
	v_add_f32_dpp v158, v158, v158 quad_perm:[2,3,0,1] row_mask:0xf bank_mask:0xf bound_ctrl:1
	v_add_f32_dpp v159, v159, v159 quad_perm:[2,3,0,1] row_mask:0xf bank_mask:0xf bound_ctrl:1
	s_nop 1
	v_add_f32_dpp v152, v152, v152 row_half_mirror row_mask:0xf bank_mask:0xf bound_ctrl:1
	v_add_f32_dpp v153, v153, v153 row_half_mirror row_mask:0xf bank_mask:0xf bound_ctrl:1
	v_add_f32_dpp v154, v154, v154 row_half_mirror row_mask:0xf bank_mask:0xf bound_ctrl:1
	v_add_f32_dpp v155, v155, v155 row_half_mirror row_mask:0xf bank_mask:0xf bound_ctrl:1
	v_add_f32_dpp v156, v156, v156 row_half_mirror row_mask:0xf bank_mask:0xf bound_ctrl:1
	v_add_f32_dpp v157, v157, v157 row_half_mirror row_mask:0xf bank_mask:0xf bound_ctrl:1
	v_add_f32_dpp v158, v158, v158 row_half_mirror row_mask:0xf bank_mask:0xf bound_ctrl:1
	v_add_f32_dpp v159, v159, v159 row_half_mirror row_mask:0xf bank_mask:0xf bound_ctrl:1
	v_fmamk_f32 v152, v152, 0x3c800000, v221
	v_fmamk_f32 v153, v153, 0x3c800000, v221
	v_fmamk_f32 v154, v154, 0x3c800000, v221
	v_fmamk_f32 v155, v155, 0x3c800000, v221
	v_fmamk_f32 v156, v156, 0x3c800000, v221
	v_fmamk_f32 v157, v157, 0x3c800000, v221
	v_fmamk_f32 v158, v158, 0x3c800000, v221
	v_fmamk_f32 v159, v159, 0x3c800000, v221
	v_rsq_f32_e32 v152, v152
	v_rsq_f32_e32 v153, v153
	v_rsq_f32_e32 v154, v154
	v_rsq_f32_e32 v155, v155
	v_rsq_f32_e32 v156, v156
	v_rsq_f32_e32 v157, v157
	v_rsq_f32_e32 v158, v158
	v_rsq_f32_e32 v159, v159
	s_cmp_gt_i32 s22, 0x3fff
	s_cbranch_scc1 .Lgn3_st0
	v_lshlrev_b32_e32 v160, 16, v64
	v_and_b32_e32 v161, 0xffff0000, v64
	v_lshlrev_b32_e32 v162, 16, v65
	v_and_b32_e32 v163, 0xffff0000, v65
	v_lshlrev_b32_e32 v164, 16, v66
	v_and_b32_e32 v165, 0xffff0000, v66
	v_lshlrev_b32_e32 v166, 16, v67
	v_and_b32_e32 v167, 0xffff0000, v67
	v_mul_f32_e32 v168, 0xbfb8aa3b, v160
	v_mul_f32_e32 v169, 0xbfb8aa3b, v161
	v_mul_f32_e32 v170, 0xbfb8aa3b, v162
	v_mul_f32_e32 v171, 0xbfb8aa3b, v163
	v_mul_f32_e32 v172, 0xbfb8aa3b, v164
	v_mul_f32_e32 v173, 0xbfb8aa3b, v165
	v_mul_f32_e32 v174, 0xbfb8aa3b, v166
	v_mul_f32_e32 v175, 0xbfb8aa3b, v167
	v_exp_f32_e32 v168, v168
	v_exp_f32_e32 v169, v169
	v_exp_f32_e32 v170, v170
	v_exp_f32_e32 v171, v171
	v_exp_f32_e32 v172, v172
	v_exp_f32_e32 v173, v173
	v_exp_f32_e32 v174, v174
	v_exp_f32_e32 v175, v175
	v_add_f32_e32 v168, 1.0, v168
	v_add_f32_e32 v169, 1.0, v169
	v_add_f32_e32 v170, 1.0, v170
	v_add_f32_e32 v171, 1.0, v171
	v_add_f32_e32 v172, 1.0, v172
	v_add_f32_e32 v173, 1.0, v173
	v_add_f32_e32 v174, 1.0, v174
	v_add_f32_e32 v175, 1.0, v175
	v_rcp_f32_e32 v168, v168
	v_rcp_f32_e32 v169, v169
	v_rcp_f32_e32 v170, v170
	v_rcp_f32_e32 v171, v171
	v_rcp_f32_e32 v172, v172
	v_rcp_f32_e32 v173, v173
	v_rcp_f32_e32 v174, v174
	v_rcp_f32_e32 v175, v175
	v_mul_f32_e32 v56, v56, v152
	v_mul_f32_e32 v57, v57, v152
	v_mul_f32_e32 v58, v58, v152
	v_mul_f32_e32 v59, v59, v152
	v_mul_f32_e32 v60, v60, v152
	v_mul_f32_e32 v61, v61, v152
	v_mul_f32_e32 v62, v62, v152
	v_mul_f32_e32 v63, v63, v152
	v_mul_f32_e32 v56, v42, v56
	v_mul_f32_e32 v57, v43, v57
	v_mul_f32_e32 v58, v44, v58
	v_mul_f32_e32 v59, v45, v59
	v_mul_f32_e32 v60, v46, v60
	v_mul_f32_e32 v61, v47, v61
	v_mul_f32_e32 v62, v48, v62
	v_mul_f32_e32 v63, v49, v63
	v_mul_f32_e32 v160, v160, v168
	v_mul_f32_e32 v161, v161, v169
	v_mul_f32_e32 v162, v162, v170
	v_mul_f32_e32 v163, v163, v171
	v_mul_f32_e32 v164, v164, v172
	v_mul_f32_e32 v165, v165, v173
	v_mul_f32_e32 v166, v166, v174
	v_mul_f32_e32 v167, v167, v175
	v_mul_f32_e32 v56, v160, v56
	v_mul_f32_e32 v57, v161, v57
	v_mul_f32_e32 v58, v162, v58
	v_mul_f32_e32 v59, v163, v59
	v_mul_f32_e32 v60, v164, v60
	v_mul_f32_e32 v61, v165, v61
	v_mul_f32_e32 v62, v166, v62
	v_mul_f32_e32 v63, v167, v63
	v_bfe_u32 v168, v56, 16, 1
	v_bfe_u32 v169, v57, 16, 1
	v_bfe_u32 v170, v58, 16, 1
	v_bfe_u32 v171, v59, 16, 1
	v_bfe_u32 v172, v60, 16, 1
	v_bfe_u32 v173, v61, 16, 1
	v_bfe_u32 v174, v62, 16, 1
	v_bfe_u32 v175, v63, 16, 1
	v_add3_u32 v56, v56, v168, s15
	v_add3_u32 v57, v57, v169, s15
	v_add3_u32 v58, v58, v170, s15
	v_add3_u32 v59, v59, v171, s15
	v_add3_u32 v60, v60, v172, s15
	v_add3_u32 v61, v61, v173, s15
	v_add3_u32 v62, v62, v174, s15
	v_add3_u32 v63, v63, v175, s15
	v_perm_b32 v176, v57, v56, s3
	v_perm_b32 v177, v59, v58, s3
	v_perm_b32 v178, v61, v60, s3
	v_perm_b32 v179, v63, v62, s3
	s_lshl_b32 s10, s22, 11
	s_add_u32 s16, s8, s10
	s_addc_u32 s17, s9, 0
	global_store_dwordx4 v41, v[176:179], s[16:17]
; __device__ __forceinline__ float bf2f(bf16 v) { return __uint_as_float(((unsigned)v) << 16); }
; __device__ __forceinline__ unsigned f2bf(float f) { unsigned u = __float_as_uint(f); return (u + 0x7fffu + ((u >> 16) & 1u)) >> 16; }
; __device__ __forceinline__ float siluf_(float x) { return x / (1.0f + __expf(-x)); }
; __device__ __forceinline__ void p4b_gdn_norm(const Ctx& c0, int l) {
;     ...
;             if (it < MPR * 8) { const int hh = it & 7, m = it >> 3; ov[u] = __builtin_nontemporal_load(OG + (size_t)m * 512 + hh * 64 + lane); zv[u] = bf2f(__builtin_nontemporal_load(H + (size_t)m * HW + HGZ + hh * 64 + lane)); } }
; #pragma unroll
;         for (int u = 0; u < 8; ++u) { const int it = it0 + u * NGW;
;             if (it < MPR * 8) { const int hh = it & 7, m = it >> 3; const float ms = wave_sum_fast(ov[u] * ov[u]) * (1.f / 64.f);
;                 MIX[(size_t)m * DM + 512 + hh * 64 + lane] = (bf16)f2bf(ov[u] * rsqrtf(ms + RMS_EPS) * nw * siluf_(zv[u])); } } }
.Lgn3_st0:
	s_cmp_gt_i32 s23, 0x3fff
	s_cbranch_scc1 .Lgn3_st1
	v_lshlrev_b32_e32 v160, 16, v76
	v_and_b32_e32 v161, 0xffff0000, v76
	v_lshlrev_b32_e32 v162, 16, v77
	v_and_b32_e32 v163, 0xffff0000, v77
	v_lshlrev_b32_e32 v164, 16, v78
	v_and_b32_e32 v165, 0xffff0000, v78
	v_lshlrev_b32_e32 v166, 16, v79
	v_and_b32_e32 v167, 0xffff0000, v79
	v_mul_f32_e32 v168, 0xbfb8aa3b, v160
	v_mul_f32_e32 v169, 0xbfb8aa3b, v161
	v_mul_f32_e32 v170, 0xbfb8aa3b, v162
	v_mul_f32_e32 v171, 0xbfb8aa3b, v163
	v_mul_f32_e32 v172, 0xbfb8aa3b, v164
	v_mul_f32_e32 v173, 0xbfb8aa3b, v165
	v_mul_f32_e32 v174, 0xbfb8aa3b, v166
	v_mul_f32_e32 v175, 0xbfb8aa3b, v167
	v_exp_f32_e32 v168, v168
	v_exp_f32_e32 v169, v169
	v_exp_f32_e32 v170, v170
	v_exp_f32_e32 v171, v171
	v_exp_f32_e32 v172, v172
	v_exp_f32_e32 v173, v173
	v_exp_f32_e32 v174, v174
	v_exp_f32_e32 v175, v175
	v_add_f32_e32 v168, 1.0, v168
	v_add_f32_e32 v169, 1.0, v169
	v_add_f32_e32 v170, 1.0, v170
	v_add_f32_e32 v171, 1.0, v171
	v_add_f32_e32 v172, 1.0, v172
	v_add_f32_e32 v173, 1.0, v173
	v_add_f32_e32 v174, 1.0, v174
	v_add_f32_e32 v175, 1.0, v175
	v_rcp_f32_e32 v168, v168
	v_rcp_f32_e32 v169, v169
	v_rcp_f32_e32 v170, v170
	v_rcp_f32_e32 v171, v171
	v_rcp_f32_e32 v172, v172
	v_rcp_f32_e32 v173, v173
	v_rcp_f32_e32 v174, v174
	v_rcp_f32_e32 v175, v175
	v_mul_f32_e32 v68, v68, v153
	v_mul_f32_e32 v69, v69, v153
	v_mul_f32_e32 v70, v70, v153
	v_mul_f32_e32 v71, v71, v153
	v_mul_f32_e32 v72, v72, v153
	v_mul_f32_e32 v73, v73, v153
	v_mul_f32_e32 v74, v74, v153
	v_mul_f32_e32 v75, v75, v153
	v_mul_f32_e32 v68, v42, v68
	v_mul_f32_e32 v69, v43, v69
	v_mul_f32_e32 v70, v44, v70
	v_mul_f32_e32 v71, v45, v71
	v_mul_f32_e32 v72, v46, v72
	v_mul_f32_e32 v73, v47, v73
	v_mul_f32_e32 v74, v48, v74
	v_mul_f32_e32 v75, v49, v75
	v_mul_f32_e32 v160, v160, v168
	v_mul_f32_e32 v161, v161, v169
	v_mul_f32_e32 v162, v162, v170
	v_mul_f32_e32 v163, v163, v171
	v_mul_f32_e32 v164, v164, v172
	v_mul_f32_e32 v165, v165, v173
	v_mul_f32_e32 v166, v166, v174
	v_mul_f32_e32 v167, v167, v175
	v_mul_f32_e32 v68, v160, v68
	v_mul_f32_e32 v69, v161, v69
	v_mul_f32_e32 v70, v162, v70
	v_mul_f32_e32 v71, v163, v71
	v_mul_f32_e32 v72, v164, v72
	v_mul_f32_e32 v73, v165, v73
	v_mul_f32_e32 v74, v166, v74
	v_mul_f32_e32 v75, v167, v75
	v_bfe_u32 v168, v68, 16, 1
	v_bfe_u32 v169, v69, 16, 1
	v_bfe_u32 v170, v70, 16, 1
	v_bfe_u32 v171, v71, 16, 1
	v_bfe_u32 v172, v72, 16, 1
	v_bfe_u32 v173, v73, 16, 1
	v_bfe_u32 v174, v74, 16, 1
	v_bfe_u32 v175, v75, 16, 1
	v_add3_u32 v68, v68, v168, s15
	v_add3_u32 v69, v69, v169, s15
	v_add3_u32 v70, v70, v170, s15
	v_add3_u32 v71, v71, v171, s15
	v_add3_u32 v72, v72, v172, s15
	v_add3_u32 v73, v73, v173, s15
	v_add3_u32 v74, v74, v174, s15
	v_add3_u32 v75, v75, v175, s15
	v_perm_b32 v176, v69, v68, s3
	v_perm_b32 v177, v71, v70, s3
	v_perm_b32 v178, v73, v72, s3
	v_perm_b32 v179, v75, v74, s3
	s_lshl_b32 s10, s23, 11
	s_add_u32 s16, s8, s10
	s_addc_u32 s17, s9, 0
	global_store_dwordx4 v41, v[176:179], s[16:17]
.Lgn3_st1:
	s_cmp_gt_i32 s24, 0x3fff
	s_cbranch_scc1 .Lgn3_st2
	v_lshlrev_b32_e32 v160, 16, v88
	v_and_b32_e32 v161, 0xffff0000, v88
	v_lshlrev_b32_e32 v162, 16, v89
	v_and_b32_e32 v163, 0xffff0000, v89
	v_lshlrev_b32_e32 v164, 16, v90
	v_and_b32_e32 v165, 0xffff0000, v90
	v_lshlrev_b32_e32 v166, 16, v91
	v_and_b32_e32 v167, 0xffff0000, v91
	v_mul_f32_e32 v168, 0xbfb8aa3b, v160
	v_mul_f32_e32 v169, 0xbfb8aa3b, v161
	v_mul_f32_e32 v170, 0xbfb8aa3b, v162
	v_mul_f32_e32 v171, 0xbfb8aa3b, v163
	v_mul_f32_e32 v172, 0xbfb8aa3b, v164
	v_mul_f32_e32 v173, 0xbfb8aa3b, v165
	v_mul_f32_e32 v174, 0xbfb8aa3b, v166
	v_mul_f32_e32 v175, 0xbfb8aa3b, v167
	v_exp_f32_e32 v168, v168
	v_exp_f32_e32 v169, v169
	v_exp_f32_e32 v170, v170
	v_exp_f32_e32 v171, v171
	v_exp_f32_e32 v172, v172
	v_exp_f32_e32 v173, v173
	v_exp_f32_e32 v174, v174
	v_exp_f32_e32 v175, v175
	v_add_f32_e32 v168, 1.0, v168
	v_add_f32_e32 v169, 1.0, v169
	v_add_f32_e32 v170, 1.0, v170
	v_add_f32_e32 v171, 1.0, v171
	v_add_f32_e32 v172, 1.0, v172
	v_add_f32_e32 v173, 1.0, v173
	v_add_f32_e32 v174, 1.0, v174
	v_add_f32_e32 v175, 1.0, v175
	v_rcp_f32_e32 v168, v168
	v_rcp_f32_e32 v169, v169
	v_rcp_f32_e32 v170, v170
	v_rcp_f32_e32 v171, v171
	v_rcp_f32_e32 v172, v172
	v_rcp_f32_e32 v173, v173
	v_rcp_f32_e32 v174, v174
	v_rcp_f32_e32 v175, v175
	v_mul_f32_e32 v80, v80, v154
	v_mul_f32_e32 v81, v81, v154
	v_mul_f32_e32 v82, v82, v154
	v_mul_f32_e32 v83, v83, v154
	v_mul_f32_e32 v84, v84, v154
	v_mul_f32_e32 v85, v85, v154
	v_mul_f32_e32 v86, v86, v154
	v_mul_f32_e32 v87, v87, v154
	v_mul_f32_e32 v80, v42, v80
	v_mul_f32_e32 v81, v43, v81
	v_mul_f32_e32 v82, v44, v82
	v_mul_f32_e32 v83, v45, v83
	v_mul_f32_e32 v84, v46, v84
	v_mul_f32_e32 v85, v47, v85
	v_mul_f32_e32 v86, v48, v86
	v_mul_f32_e32 v87, v49, v87
	v_mul_f32_e32 v160, v160, v168
	v_mul_f32_e32 v161, v161, v169
	v_mul_f32_e32 v162, v162, v170
	v_mul_f32_e32 v163, v163, v171
	v_mul_f32_e32 v164, v164, v172
	v_mul_f32_e32 v165, v165, v173
	v_mul_f32_e32 v166, v166, v174
	v_mul_f32_e32 v167, v167, v175
	v_mul_f32_e32 v80, v160, v80
	v_mul_f32_e32 v81, v161, v81
	v_mul_f32_e32 v82, v162, v82
	v_mul_f32_e32 v83, v163, v83
	v_mul_f32_e32 v84, v164, v84
	v_mul_f32_e32 v85, v165, v85
	v_mul_f32_e32 v86, v166, v86
	v_mul_f32_e32 v87, v167, v87
	v_bfe_u32 v168, v80, 16, 1
	v_bfe_u32 v169, v81, 16, 1
	v_bfe_u32 v170, v82, 16, 1
	v_bfe_u32 v171, v83, 16, 1
	v_bfe_u32 v172, v84, 16, 1
	v_bfe_u32 v173, v85, 16, 1
	v_bfe_u32 v174, v86, 16, 1
	v_bfe_u32 v175, v87, 16, 1
	v_add3_u32 v80, v80, v168, s15
	v_add3_u32 v81, v81, v169, s15
	v_add3_u32 v82, v82, v170, s15
	v_add3_u32 v83, v83, v171, s15
	v_add3_u32 v84, v84, v172, s15
	v_add3_u32 v85, v85, v173, s15
	v_add3_u32 v86, v86, v174, s15
	v_add3_u32 v87, v87, v175, s15
	v_perm_b32 v176, v81, v80, s3
	v_perm_b32 v177, v83, v82, s3
	v_perm_b32 v178, v85, v84, s3
	v_perm_b32 v179, v87, v86, s3
	s_lshl_b32 s10, s24, 11
	s_add_u32 s16, s8, s10
	s_addc_u32 s17, s9, 0
	global_store_dwordx4 v41, v[176:179], s[16:17]
; __device__ __forceinline__ float bf2f(bf16 v) { return __uint_as_float(((unsigned)v) << 16); }
; __device__ __forceinline__ unsigned f2bf(float f) { unsigned u = __float_as_uint(f); return (u + 0x7fffu + ((u >> 16) & 1u)) >> 16; }
; __device__ __forceinline__ float siluf_(float x) { return x / (1.0f + __expf(-x)); }
; __device__ __forceinline__ void p4b_gdn_norm(const Ctx& c0, int l) {
;     ...
;             if (it < MPR * 8) { const int hh = it & 7, m = it >> 3; ov[u] = __builtin_nontemporal_load(OG + (size_t)m * 512 + hh * 64 + lane); zv[u] = bf2f(__builtin_nontemporal_load(H + (size_t)m * HW + HGZ + hh * 64 + lane)); } }
; #pragma unroll
;         for (int u = 0; u < 8; ++u) { const int it = it0 + u * NGW;
;             if (it < MPR * 8) { const int hh = it & 7, m = it >> 3; const float ms = wave_sum_fast(ov[u] * ov[u]) * (1.f / 64.f);
;                 MIX[(size_t)m * DM + 512 + hh * 64 + lane] = (bf16)f2bf(ov[u] * rsqrtf(ms + RMS_EPS) * nw * siluf_(zv[u])); } } }
.Lgn3_st2:
	s_cmp_gt_i32 s25, 0x3fff
	s_cbranch_scc1 .Lgn3_st3
	v_lshlrev_b32_e32 v160, 16, v100
	v_and_b32_e32 v161, 0xffff0000, v100
	v_lshlrev_b32_e32 v162, 16, v101
	v_and_b32_e32 v163, 0xffff0000, v101
	v_lshlrev_b32_e32 v164, 16, v102
	v_and_b32_e32 v165, 0xffff0000, v102
	v_lshlrev_b32_e32 v166, 16, v103
	v_and_b32_e32 v167, 0xffff0000, v103
	v_mul_f32_e32 v168, 0xbfb8aa3b, v160
	v_mul_f32_e32 v169, 0xbfb8aa3b, v161
	v_mul_f32_e32 v170, 0xbfb8aa3b, v162
	v_mul_f32_e32 v171, 0xbfb8aa3b, v163
	v_mul_f32_e32 v172, 0xbfb8aa3b, v164
	v_mul_f32_e32 v173, 0xbfb8aa3b, v165
	v_mul_f32_e32 v174, 0xbfb8aa3b, v166
	v_mul_f32_e32 v175, 0xbfb8aa3b, v167
	v_exp_f32_e32 v168, v168
	v_exp_f32_e32 v169, v169
	v_exp_f32_e32 v170, v170
	v_exp_f32_e32 v171, v171
	v_exp_f32_e32 v172, v172
	v_exp_f32_e32 v173, v173
	v_exp_f32_e32 v174, v174
	v_exp_f32_e32 v175, v175
	v_add_f32_e32 v168, 1.0, v168
	v_add_f32_e32 v169, 1.0, v169
	v_add_f32_e32 v170, 1.0, v170
	v_add_f32_e32 v171, 1.0, v171
	v_add_f32_e32 v172, 1.0, v172
	v_add_f32_e32 v173, 1.0, v173
	v_add_f32_e32 v174, 1.0, v174
	v_add_f32_e32 v175, 1.0, v175
	v_rcp_f32_e32 v168, v168
	v_rcp_f32_e32 v169, v169
	v_rcp_f32_e32 v170, v170
	v_rcp_f32_e32 v171, v171
	v_rcp_f32_e32 v172, v172
	v_rcp_f32_e32 v173, v173
	v_rcp_f32_e32 v174, v174
	v_rcp_f32_e32 v175, v175
	v_mul_f32_e32 v92, v92, v155
	v_mul_f32_e32 v93, v93, v155
	v_mul_f32_e32 v94, v94, v155
	v_mul_f32_e32 v95, v95, v155
	v_mul_f32_e32 v96, v96, v155
	v_mul_f32_e32 v97, v97, v155
	v_mul_f32_e32 v98, v98, v155
	v_mul_f32_e32 v99, v99, v155
	v_mul_f32_e32 v92, v42, v92
	v_mul_f32_e32 v93, v43, v93
	v_mul_f32_e32 v94, v44, v94
	v_mul_f32_e32 v95, v45, v95
	v_mul_f32_e32 v96, v46, v96
	v_mul_f32_e32 v97, v47, v97
	v_mul_f32_e32 v98, v48, v98
	v_mul_f32_e32 v99, v49, v99
	v_mul_f32_e32 v160, v160, v168
	v_mul_f32_e32 v161, v161, v169
	v_mul_f32_e32 v162, v162, v170
	v_mul_f32_e32 v163, v163, v171
	v_mul_f32_e32 v164, v164, v172
	v_mul_f32_e32 v165, v165, v173
	v_mul_f32_e32 v166, v166, v174
	v_mul_f32_e32 v167, v167, v175
	v_mul_f32_e32 v92, v160, v92
	v_mul_f32_e32 v93, v161, v93
	v_mul_f32_e32 v94, v162, v94
	v_mul_f32_e32 v95, v163, v95
	v_mul_f32_e32 v96, v164, v96
	v_mul_f32_e32 v97, v165, v97
	v_mul_f32_e32 v98, v166, v98
	v_mul_f32_e32 v99, v167, v99
	v_bfe_u32 v168, v92, 16, 1
	v_bfe_u32 v169, v93, 16, 1
	v_bfe_u32 v170, v94, 16, 1
	v_bfe_u32 v171, v95, 16, 1
	v_bfe_u32 v172, v96, 16, 1
	v_bfe_u32 v173, v97, 16, 1
	v_bfe_u32 v174, v98, 16, 1
	v_bfe_u32 v175, v99, 16, 1
	v_add3_u32 v92, v92, v168, s15
	v_add3_u32 v93, v93, v169, s15
	v_add3_u32 v94, v94, v170, s15
	v_add3_u32 v95, v95, v171, s15
	v_add3_u32 v96, v96, v172, s15
	v_add3_u32 v97, v97, v173, s15
	v_add3_u32 v98, v98, v174, s15
	v_add3_u32 v99, v99, v175, s15
	v_perm_b32 v176, v93, v92, s3
	v_perm_b32 v177, v95, v94, s3
	v_perm_b32 v178, v97, v96, s3
	v_perm_b32 v179, v99, v98, s3
	s_lshl_b32 s10, s25, 11
	s_add_u32 s16, s8, s10
	s_addc_u32 s17, s9, 0
	global_store_dwordx4 v41, v[176:179], s[16:17]
.Lgn3_st3:
	s_cmp_gt_i32 s26, 0x3fff
	s_cbranch_scc1 .Lgn3_st4
	v_lshlrev_b32_e32 v160, 16, v112
	v_and_b32_e32 v161, 0xffff0000, v112
	v_lshlrev_b32_e32 v162, 16, v113
	v_and_b32_e32 v163, 0xffff0000, v113
	v_lshlrev_b32_e32 v164, 16, v114
	v_and_b32_e32 v165, 0xffff0000, v114
	v_lshlrev_b32_e32 v166, 16, v115
	v_and_b32_e32 v167, 0xffff0000, v115
	v_mul_f32_e32 v168, 0xbfb8aa3b, v160
	v_mul_f32_e32 v169, 0xbfb8aa3b, v161
	v_mul_f32_e32 v170, 0xbfb8aa3b, v162
	v_mul_f32_e32 v171, 0xbfb8aa3b, v163
	v_mul_f32_e32 v172, 0xbfb8aa3b, v164
	v_mul_f32_e32 v173, 0xbfb8aa3b, v165
	v_mul_f32_e32 v174, 0xbfb8aa3b, v166
	v_mul_f32_e32 v175, 0xbfb8aa3b, v167
	v_exp_f32_e32 v168, v168
	v_exp_f32_e32 v169, v169
	v_exp_f32_e32 v170, v170
	v_exp_f32_e32 v171, v171
	v_exp_f32_e32 v172, v172
	v_exp_f32_e32 v173, v173
	v_exp_f32_e32 v174, v174
	v_exp_f32_e32 v175, v175
	v_add_f32_e32 v168, 1.0, v168
	v_add_f32_e32 v169, 1.0, v169
	v_add_f32_e32 v170, 1.0, v170
	v_add_f32_e32 v171, 1.0, v171
	v_add_f32_e32 v172, 1.0, v172
	v_add_f32_e32 v173, 1.0, v173
	v_add_f32_e32 v174, 1.0, v174
	v_add_f32_e32 v175, 1.0, v175
	v_rcp_f32_e32 v168, v168
	v_rcp_f32_e32 v169, v169
	v_rcp_f32_e32 v170, v170
	v_rcp_f32_e32 v171, v171
	v_rcp_f32_e32 v172, v172
	v_rcp_f32_e32 v173, v173
	v_rcp_f32_e32 v174, v174
	v_rcp_f32_e32 v175, v175
	v_mul_f32_e32 v104, v104, v156
	v_mul_f32_e32 v105, v105, v156
	v_mul_f32_e32 v106, v106, v156
	v_mul_f32_e32 v107, v107, v156
	v_mul_f32_e32 v108, v108, v156
	v_mul_f32_e32 v109, v109, v156
	v_mul_f32_e32 v110, v110, v156
	v_mul_f32_e32 v111, v111, v156
	v_mul_f32_e32 v104, v42, v104
	v_mul_f32_e32 v105, v43, v105
	v_mul_f32_e32 v106, v44, v106
	v_mul_f32_e32 v107, v45, v107
	v_mul_f32_e32 v108, v46, v108
	v_mul_f32_e32 v109, v47, v109
	v_mul_f32_e32 v110, v48, v110
	v_mul_f32_e32 v111, v49, v111
	v_mul_f32_e32 v160, v160, v168
	v_mul_f32_e32 v161, v161, v169
	v_mul_f32_e32 v162, v162, v170
	v_mul_f32_e32 v163, v163, v171
	v_mul_f32_e32 v164, v164, v172
	v_mul_f32_e32 v165, v165, v173
	v_mul_f32_e32 v166, v166, v174
	v_mul_f32_e32 v167, v167, v175
	v_mul_f32_e32 v104, v160, v104
	v_mul_f32_e32 v105, v161, v105
	v_mul_f32_e32 v106, v162, v106
	v_mul_f32_e32 v107, v163, v107
	v_mul_f32_e32 v108, v164, v108
	v_mul_f32_e32 v109, v165, v109
	v_mul_f32_e32 v110, v166, v110
	v_mul_f32_e32 v111, v167, v111
	v_bfe_u32 v168, v104, 16, 1
	v_bfe_u32 v169, v105, 16, 1
	v_bfe_u32 v170, v106, 16, 1
	v_bfe_u32 v171, v107, 16, 1
	v_bfe_u32 v172, v108, 16, 1
	v_bfe_u32 v173, v109, 16, 1
	v_bfe_u32 v174, v110, 16, 1
	v_bfe_u32 v175, v111, 16, 1
	v_add3_u32 v104, v104, v168, s15
	v_add3_u32 v105, v105, v169, s15
	v_add3_u32 v106, v106, v170, s15
	v_add3_u32 v107, v107, v171, s15
	v_add3_u32 v108, v108, v172, s15
	v_add3_u32 v109, v109, v173, s15
	v_add3_u32 v110, v110, v174, s15
	v_add3_u32 v111, v111, v175, s15
	v_perm_b32 v176, v105, v104, s3
	v_perm_b32 v177, v107, v106, s3
	v_perm_b32 v178, v109, v108, s3
	v_perm_b32 v179, v111, v110, s3
	s_lshl_b32 s10, s26, 11
	s_add_u32 s16, s8, s10
	s_addc_u32 s17, s9, 0
	global_store_dwordx4 v41, v[176:179], s[16:17]
; __device__ __forceinline__ float bf2f(bf16 v) { return __uint_as_float(((unsigned)v) << 16); }
; __device__ __forceinline__ unsigned f2bf(float f) { unsigned u = __float_as_uint(f); return (u + 0x7fffu + ((u >> 16) & 1u)) >> 16; }
; __device__ __forceinline__ float siluf_(float x) { return x / (1.0f + __expf(-x)); }
; __device__ __forceinline__ void p4b_gdn_norm(const Ctx& c0, int l) {
;     ...
;     for (int it0 = gw; it0 < MPR * 8; it0 += 8 * NGW) {
;         float ov[8], zv[8];
; #pragma unroll
;         for (int u = 0; u < 8; ++u) { const int it = it0 + u * NGW; ov[u] = 0.f; zv[u] = 0.f;
;             if (it < MPR * 8) { const int hh = it & 7, m = it >> 3; ov[u] = __builtin_nontemporal_load(OG + (size_t)m * 512 + hh * 64 + lane); zv[u] = bf2f(__builtin_nontemporal_load(H + (size_t)m * HW + HGZ + hh * 64 + lane)); } }
; #pragma unroll
;         for (int u = 0; u < 8; ++u) { const int it = it0 + u * NGW;
;             if (it < MPR * 8) { const int hh = it & 7, m = it >> 3; const float ms = wave_sum_fast(ov[u] * ov[u]) * (1.f / 64.f);
;                 MIX[(size_t)m * DM + 512 + hh * 64 + lane] = (bf16)f2bf(ov[u] * rsqrtf(ms + RMS_EPS) * nw * siluf_(zv[u])); } } }
.Lgn3_st4:
	s_cmp_gt_i32 s27, 0x3fff
	s_cbranch_scc1 .Lgn3_st5
	v_lshlrev_b32_e32 v160, 16, v124
	v_and_b32_e32 v161, 0xffff0000, v124
	v_lshlrev_b32_e32 v162, 16, v125
	v_and_b32_e32 v163, 0xffff0000, v125
	v_lshlrev_b32_e32 v164, 16, v126
	v_and_b32_e32 v165, 0xffff0000, v126
	v_lshlrev_b32_e32 v166, 16, v127
	v_and_b32_e32 v167, 0xffff0000, v127
	v_mul_f32_e32 v168, 0xbfb8aa3b, v160
	v_mul_f32_e32 v169, 0xbfb8aa3b, v161
	v_mul_f32_e32 v170, 0xbfb8aa3b, v162
	v_mul_f32_e32 v171, 0xbfb8aa3b, v163
	v_mul_f32_e32 v172, 0xbfb8aa3b, v164
	v_mul_f32_e32 v173, 0xbfb8aa3b, v165
	v_mul_f32_e32 v174, 0xbfb8aa3b, v166
	v_mul_f32_e32 v175, 0xbfb8aa3b, v167
	v_exp_f32_e32 v168, v168
	v_exp_f32_e32 v169, v169
	v_exp_f32_e32 v170, v170
	v_exp_f32_e32 v171, v171
	v_exp_f32_e32 v172, v172
	v_exp_f32_e32 v173, v173
	v_exp_f32_e32 v174, v174
	v_exp_f32_e32 v175, v175
	v_add_f32_e32 v168, 1.0, v168
	v_add_f32_e32 v169, 1.0, v169
	v_add_f32_e32 v170, 1.0, v170
	v_add_f32_e32 v171, 1.0, v171
	v_add_f32_e32 v172, 1.0, v172
	v_add_f32_e32 v173, 1.0, v173
	v_add_f32_e32 v174, 1.0, v174
	v_add_f32_e32 v175, 1.0, v175
	v_rcp_f32_e32 v168, v168
	v_rcp_f32_e32 v169, v169
	v_rcp_f32_e32 v170, v170
	v_rcp_f32_e32 v171, v171
	v_rcp_f32_e32 v172, v172
	v_rcp_f32_e32 v173, v173
	v_rcp_f32_e32 v174, v174
	v_rcp_f32_e32 v175, v175
	v_mul_f32_e32 v116, v116, v157
	v_mul_f32_e32 v117, v117, v157
	v_mul_f32_e32 v118, v118, v157
	v_mul_f32_e32 v119, v119, v157
	v_mul_f32_e32 v120, v120, v157
	v_mul_f32_e32 v121, v121, v157
	v_mul_f32_e32 v122, v122, v157
	v_mul_f32_e32 v123, v123, v157
	v_mul_f32_e32 v116, v42, v116
	v_mul_f32_e32 v117, v43, v117
	v_mul_f32_e32 v118, v44, v118
	v_mul_f32_e32 v119, v45, v119
	v_mul_f32_e32 v120, v46, v120
	v_mul_f32_e32 v121, v47, v121
	v_mul_f32_e32 v122, v48, v122
	v_mul_f32_e32 v123, v49, v123
	v_mul_f32_e32 v160, v160, v168
	v_mul_f32_e32 v161, v161, v169
	v_mul_f32_e32 v162, v162, v170
	v_mul_f32_e32 v163, v163, v171
	v_mul_f32_e32 v164, v164, v172
	v_mul_f32_e32 v165, v165, v173
	v_mul_f32_e32 v166, v166, v174
	v_mul_f32_e32 v167, v167, v175
	v_mul_f32_e32 v116, v160, v116
	v_mul_f32_e32 v117, v161, v117
	v_mul_f32_e32 v118, v162, v118
	v_mul_f32_e32 v119, v163, v119
	v_mul_f32_e32 v120, v164, v120
	v_mul_f32_e32 v121, v165, v121
	v_mul_f32_e32 v122, v166, v122
	v_mul_f32_e32 v123, v167, v123
	v_bfe_u32 v168, v116, 16, 1
	v_bfe_u32 v169, v117, 16, 1
	v_bfe_u32 v170, v118, 16, 1
	v_bfe_u32 v171, v119, 16, 1
	v_bfe_u32 v172, v120, 16, 1
	v_bfe_u32 v173, v121, 16, 1
	v_bfe_u32 v174, v122, 16, 1
	v_bfe_u32 v175, v123, 16, 1
	v_add3_u32 v116, v116, v168, s15
	v_add3_u32 v117, v117, v169, s15
	v_add3_u32 v118, v118, v170, s15
	v_add3_u32 v119, v119, v171, s15
	v_add3_u32 v120, v120, v172, s15
	v_add3_u32 v121, v121, v173, s15
	v_add3_u32 v122, v122, v174, s15
	v_add3_u32 v123, v123, v175, s15
	v_perm_b32 v176, v117, v116, s3
	v_perm_b32 v177, v119, v118, s3
	v_perm_b32 v178, v121, v120, s3
	v_perm_b32 v179, v123, v122, s3
	s_lshl_b32 s10, s27, 11
	s_add_u32 s16, s8, s10
	s_addc_u32 s17, s9, 0
	global_store_dwordx4 v41, v[176:179], s[16:17]
.Lgn3_st5:
	s_cmp_gt_i32 s28, 0x3fff
	s_cbranch_scc1 .Lgn3_st6
	v_lshlrev_b32_e32 v160, 16, v136
	v_and_b32_e32 v161, 0xffff0000, v136
	v_lshlrev_b32_e32 v162, 16, v137
	v_and_b32_e32 v163, 0xffff0000, v137
	v_lshlrev_b32_e32 v164, 16, v138
	v_and_b32_e32 v165, 0xffff0000, v138
	v_lshlrev_b32_e32 v166, 16, v139
	v_and_b32_e32 v167, 0xffff0000, v139
	v_mul_f32_e32 v168, 0xbfb8aa3b, v160
	v_mul_f32_e32 v169, 0xbfb8aa3b, v161
	v_mul_f32_e32 v170, 0xbfb8aa3b, v162
	v_mul_f32_e32 v171, 0xbfb8aa3b, v163
	v_mul_f32_e32 v172, 0xbfb8aa3b, v164
	v_mul_f32_e32 v173, 0xbfb8aa3b, v165
	v_mul_f32_e32 v174, 0xbfb8aa3b, v166
	v_mul_f32_e32 v175, 0xbfb8aa3b, v167
	v_exp_f32_e32 v168, v168
	v_exp_f32_e32 v169, v169
	v_exp_f32_e32 v170, v170
	v_exp_f32_e32 v171, v171
	v_exp_f32_e32 v172, v172
	v_exp_f32_e32 v173, v173
	v_exp_f32_e32 v174, v174
	v_exp_f32_e32 v175, v175
	v_add_f32_e32 v168, 1.0, v168
	v_add_f32_e32 v169, 1.0, v169
	v_add_f32_e32 v170, 1.0, v170
	v_add_f32_e32 v171, 1.0, v171
	v_add_f32_e32 v172, 1.0, v172
	v_add_f32_e32 v173, 1.0, v173
	v_add_f32_e32 v174, 1.0, v174
	v_add_f32_e32 v175, 1.0, v175
	v_rcp_f32_e32 v168, v168
	v_rcp_f32_e32 v169, v169
	v_rcp_f32_e32 v170, v170
	v_rcp_f32_e32 v171, v171
	v_rcp_f32_e32 v172, v172
	v_rcp_f32_e32 v173, v173
	v_rcp_f32_e32 v174, v174
	v_rcp_f32_e32 v175, v175
	v_mul_f32_e32 v128, v128, v158
	v_mul_f32_e32 v129, v129, v158
	v_mul_f32_e32 v130, v130, v158
	v_mul_f32_e32 v131, v131, v158
	v_mul_f32_e32 v132, v132, v158
	v_mul_f32_e32 v133, v133, v158
	v_mul_f32_e32 v134, v134, v158
	v_mul_f32_e32 v135, v135, v158
	v_mul_f32_e32 v128, v42, v128
	v_mul_f32_e32 v129, v43, v129
	v_mul_f32_e32 v130, v44, v130
	v_mul_f32_e32 v131, v45, v131
	v_mul_f32_e32 v132, v46, v132
	v_mul_f32_e32 v133, v47, v133
	v_mul_f32_e32 v134, v48, v134
	v_mul_f32_e32 v135, v49, v135
	v_mul_f32_e32 v160, v160, v168
	v_mul_f32_e32 v161, v161, v169
	v_mul_f32_e32 v162, v162, v170
	v_mul_f32_e32 v163, v163, v171
	v_mul_f32_e32 v164, v164, v172
	v_mul_f32_e32 v165, v165, v173
	v_mul_f32_e32 v166, v166, v174
	v_mul_f32_e32 v167, v167, v175
	v_mul_f32_e32 v128, v160, v128
	v_mul_f32_e32 v129, v161, v129
	v_mul_f32_e32 v130, v162, v130
	v_mul_f32_e32 v131, v163, v131
	v_mul_f32_e32 v132, v164, v132
	v_mul_f32_e32 v133, v165, v133
	v_mul_f32_e32 v134, v166, v134
	v_mul_f32_e32 v135, v167, v135
	v_bfe_u32 v168, v128, 16, 1
	v_bfe_u32 v169, v129, 16, 1
	v_bfe_u32 v170, v130, 16, 1
	v_bfe_u32 v171, v131, 16, 1
	v_bfe_u32 v172, v132, 16, 1
	v_bfe_u32 v173, v133, 16, 1
	v_bfe_u32 v174, v134, 16, 1
	v_bfe_u32 v175, v135, 16, 1
	v_add3_u32 v128, v128, v168, s15
	v_add3_u32 v129, v129, v169, s15
	v_add3_u32 v130, v130, v170, s15
	v_add3_u32 v131, v131, v171, s15
	v_add3_u32 v132, v132, v172, s15
	v_add3_u32 v133, v133, v173, s15
	v_add3_u32 v134, v134, v174, s15
	v_add3_u32 v135, v135, v175, s15
	v_perm_b32 v176, v129, v128, s3
	v_perm_b32 v177, v131, v130, s3
	v_perm_b32 v178, v133, v132, s3
	v_perm_b32 v179, v135, v134, s3
	s_lshl_b32 s10, s28, 11
	s_add_u32 s16, s8, s10
	s_addc_u32 s17, s9, 0
	global_store_dwordx4 v41, v[176:179], s[16:17]
; __device__ __forceinline__ float bf2f(bf16 v) { return __uint_as_float(((unsigned)v) << 16); }
; __device__ __forceinline__ unsigned f2bf(float f) { unsigned u = __float_as_uint(f); return (u + 0x7fffu + ((u >> 16) & 1u)) >> 16; }
; __device__ __forceinline__ float siluf_(float x) { return x / (1.0f + __expf(-x)); }
; __device__ __forceinline__ void p4b_gdn_norm(const Ctx& c0, int l) {
;     ...
;     for (int it0 = gw; it0 < MPR * 8; it0 += 8 * NGW) {
;         float ov[8], zv[8];
; #pragma unroll
;         for (int u = 0; u < 8; ++u) { const int it = it0 + u * NGW; ov[u] = 0.f; zv[u] = 0.f;
;             if (it < MPR * 8) { const int hh = it & 7, m = it >> 3; ov[u] = __builtin_nontemporal_load(OG + (size_t)m * 512 + hh * 64 + lane); zv[u] = bf2f(__builtin_nontemporal_load(H + (size_t)m * HW + HGZ + hh * 64 + lane)); } }
; #pragma unroll
;         for (int u = 0; u < 8; ++u) { const int it = it0 + u * NGW;
;             if (it < MPR * 8) { const int hh = it & 7, m = it >> 3; const float ms = wave_sum_fast(ov[u] * ov[u]) * (1.f / 64.f);
;                 MIX[(size_t)m * DM + 512 + hh * 64 + lane] = (bf16)f2bf(ov[u] * rsqrtf(ms + RMS_EPS) * nw * siluf_(zv[u])); } } }
.Lgn3_st6:
	s_cmp_gt_i32 s29, 0x3fff
	s_cbranch_scc1 .Lgn3_st7
	v_lshlrev_b32_e32 v160, 16, v148
	v_and_b32_e32 v161, 0xffff0000, v148
	v_lshlrev_b32_e32 v162, 16, v149
	v_and_b32_e32 v163, 0xffff0000, v149
	v_lshlrev_b32_e32 v164, 16, v150
	v_and_b32_e32 v165, 0xffff0000, v150
	v_lshlrev_b32_e32 v166, 16, v151
	v_and_b32_e32 v167, 0xffff0000, v151
	v_mul_f32_e32 v168, 0xbfb8aa3b, v160
	v_mul_f32_e32 v169, 0xbfb8aa3b, v161
	v_mul_f32_e32 v170, 0xbfb8aa3b, v162
	v_mul_f32_e32 v171, 0xbfb8aa3b, v163
	v_mul_f32_e32 v172, 0xbfb8aa3b, v164
	v_mul_f32_e32 v173, 0xbfb8aa3b, v165
	v_mul_f32_e32 v174, 0xbfb8aa3b, v166
	v_mul_f32_e32 v175, 0xbfb8aa3b, v167
	v_exp_f32_e32 v168, v168
	v_exp_f32_e32 v169, v169
	v_exp_f32_e32 v170, v170
	v_exp_f32_e32 v171, v171
	v_exp_f32_e32 v172, v172
	v_exp_f32_e32 v173, v173
	v_exp_f32_e32 v174, v174
	v_exp_f32_e32 v175, v175
	v_add_f32_e32 v168, 1.0, v168
	v_add_f32_e32 v169, 1.0, v169
	v_add_f32_e32 v170, 1.0, v170
	v_add_f32_e32 v171, 1.0, v171
	v_add_f32_e32 v172, 1.0, v172
	v_add_f32_e32 v173, 1.0, v173
	v_add_f32_e32 v174, 1.0, v174
	v_add_f32_e32 v175, 1.0, v175
	v_rcp_f32_e32 v168, v168
	v_rcp_f32_e32 v169, v169
	v_rcp_f32_e32 v170, v170
	v_rcp_f32_e32 v171, v171
	v_rcp_f32_e32 v172, v172
	v_rcp_f32_e32 v173, v173
	v_rcp_f32_e32 v174, v174
	v_rcp_f32_e32 v175, v175
	v_mul_f32_e32 v140, v140, v159
	v_mul_f32_e32 v141, v141, v159
	v_mul_f32_e32 v142, v142, v159
	v_mul_f32_e32 v143, v143, v159
	v_mul_f32_e32 v144, v144, v159
	v_mul_f32_e32 v145, v145, v159
	v_mul_f32_e32 v146, v146, v159
	v_mul_f32_e32 v147, v147, v159
	v_mul_f32_e32 v140, v42, v140
	v_mul_f32_e32 v141, v43, v141
	v_mul_f32_e32 v142, v44, v142
	v_mul_f32_e32 v143, v45, v143
	v_mul_f32_e32 v144, v46, v144
	v_mul_f32_e32 v145, v47, v145
	v_mul_f32_e32 v146, v48, v146
	v_mul_f32_e32 v147, v49, v147
	v_mul_f32_e32 v160, v160, v168
	v_mul_f32_e32 v161, v161, v169
	v_mul_f32_e32 v162, v162, v170
	v_mul_f32_e32 v163, v163, v171
	v_mul_f32_e32 v164, v164, v172
	v_mul_f32_e32 v165, v165, v173
	v_mul_f32_e32 v166, v166, v174
	v_mul_f32_e32 v167, v167, v175
	v_mul_f32_e32 v140, v160, v140
	v_mul_f32_e32 v141, v161, v141
	v_mul_f32_e32 v142, v162, v142
	v_mul_f32_e32 v143, v163, v143
	v_mul_f32_e32 v144, v164, v144
	v_mul_f32_e32 v145, v165, v145
	v_mul_f32_e32 v146, v166, v146
	v_mul_f32_e32 v147, v167, v147
	v_bfe_u32 v168, v140, 16, 1
	v_bfe_u32 v169, v141, 16, 1
	v_bfe_u32 v170, v142, 16, 1
	v_bfe_u32 v171, v143, 16, 1
	v_bfe_u32 v172, v144, 16, 1
	v_bfe_u32 v173, v145, 16, 1
	v_bfe_u32 v174, v146, 16, 1
	v_bfe_u32 v175, v147, 16, 1
	v_add3_u32 v140, v140, v168, s15
	v_add3_u32 v141, v141, v169, s15
	v_add3_u32 v142, v142, v170, s15
	v_add3_u32 v143, v143, v171, s15
	v_add3_u32 v144, v144, v172, s15
	v_add3_u32 v145, v145, v173, s15
	v_add3_u32 v146, v146, v174, s15
	v_add3_u32 v147, v147, v175, s15
	v_perm_b32 v176, v141, v140, s3
	v_perm_b32 v177, v143, v142, s3
	v_perm_b32 v178, v145, v144, s3
	v_perm_b32 v179, v147, v146, s3
	s_lshl_b32 s10, s29, 11
	s_add_u32 s16, s8, s10
	s_addc_u32 s17, s9, 0
	global_store_dwordx4 v41, v[176:179], s[16:17]
.Lgn3_st7:
	s_lshl_b32 s10, s2, 3
	s_add_i32 s12, s12, s10
	s_cmp_lt_i32 s12, 0x4000
	s_cbranch_scc1 .Lgn3_pass
	s_branch .LBB0_1462
